# attention epilogue differential combine: all LDS reads first, then fmas, then writes
# baseline (speedup 1.0000x reference)
.LBB0_299:
	s_andn2_b64 vcc, exec, s[0:1]
	s_waitcnt lgkmcnt(0)
	s_barrier
	s_cbranch_vccnz .LBB0_266
	v_add_u32_e32 v143, 0x400, v82
	v_add_u32_e32 v142, 0x1000, v82
	v_add_u32_e32 v141, 0x1400, v82
	v_add_u32_e32 v140, 0x2000, v82
	v_add_u32_e32 v139, 0x2400, v82
	v_add_u32_e32 v138, 0x3000, v82
	v_add_u32_e32 v137, 0x3200, v82
	v_add_u32_e32 v136, 0x3400, v82
	v_add_u32_e32 v135, 0x3600, v82
	ds_read2_b32 v[84:85], v82 offset0:0 offset1:32
	ds_read2_b32 v[86:87], v82 offset0:132 offset1:164
	ds_read2_b32 v[88:89], v142 offset0:164 offset1:196
	ds_read2_b32 v[90:91], v143 offset0:8 offset1:40
	ds_read2_b32 v[92:93], v143 offset0:140 offset1:172
	ds_read2_b32 v[94:95], v141 offset0:172 offset1:204
	ds_read2_b32 v[96:97], v142 offset0:32 offset1:64
	ds_read2_b32 v[98:99], v140 offset0:196 offset1:228
	ds_read2_b32 v[100:101], v139 offset0:204 offset1:236
	ds_read2_b32 v[102:103], v141 offset0:40 offset1:72
	ds_read2_b32 v[104:105], v140 offset0:64 offset1:96
	ds_read2_b32 v[106:107], v137 offset0:100 offset1:132
	ds_read2_b32 v[108:109], v139 offset0:72 offset1:104
	ds_read2_b32 v[110:111], v138 offset0:96 offset1:128
	ds_read2_b32 v[112:113], v136 offset0:104 offset1:136
	ds_read2_b32 v[114:115], v135 offset0:108 offset1:140
	s_waitcnt lgkmcnt(0)
	v_fma_f32 v84, v50, v66, -v84
	v_fma_f32 v85, v34, v66, -v85
	v_fma_f32 v86, v51, v70, -v86
	v_fma_f32 v87, v35, v70, -v87
	v_fma_f32 v88, v55, v73, -v88
	v_fma_f32 v89, v39, v73, -v89
	v_fma_f32 v90, v52, v69, -v90
	v_fma_f32 v91, v36, v69, -v91
	v_fma_f32 v92, v53, v68, -v92
	v_fma_f32 v93, v37, v68, -v93
	v_fma_f32 v94, v57, v71, -v94
	v_fma_f32 v95, v41, v71, -v95
	v_fma_f32 v96, v54, v67, -v96
	v_fma_f32 v97, v38, v67, -v97
	v_fma_f32 v98, v59, v76, -v98
	v_fma_f32 v99, v43, v76, -v99
	v_fma_f32 v100, v61, v74, -v100
	v_fma_f32 v101, v45, v74, -v101
	v_fma_f32 v102, v56, v72, -v102
	v_fma_f32 v103, v40, v72, -v103
	v_fma_f32 v104, v58, v77, -v104
	v_fma_f32 v105, v42, v77, -v105
	v_fma_f32 v106, v63, v80, -v106
	v_fma_f32 v107, v47, v80, -v107
	v_fma_f32 v108, v60, v75, -v108
	v_fma_f32 v109, v44, v75, -v109
	v_fma_f32 v110, v62, v81, -v110
	v_fma_f32 v111, v46, v81, -v111
	v_fma_f32 v112, v64, v79, -v112
	v_fma_f32 v113, v48, v79, -v113
	v_fma_f32 v114, v65, v78, -v114
	v_fma_f32 v115, v49, v78, -v115
	ds_write2_b32 v82, v84, v85 offset0:0 offset1:32
	ds_write2_b32 v82, v86, v87 offset0:132 offset1:164
	ds_write2_b32 v142, v88, v89 offset0:164 offset1:196
	ds_write2_b32 v143, v90, v91 offset0:8 offset1:40
	ds_write2_b32 v143, v92, v93 offset0:140 offset1:172
	ds_write2_b32 v141, v94, v95 offset0:172 offset1:204
	ds_write2_b32 v142, v96, v97 offset0:32 offset1:64
	ds_write2_b32 v140, v98, v99 offset0:196 offset1:228
	ds_write2_b32 v139, v100, v101 offset0:204 offset1:236
	ds_write2_b32 v141, v102, v103 offset0:40 offset1:72
	ds_write2_b32 v140, v104, v105 offset0:64 offset1:96
	ds_write2_b32 v137, v106, v107 offset0:100 offset1:132
	ds_write2_b32 v139, v108, v109 offset0:72 offset1:104
	ds_write2_b32 v138, v110, v111 offset0:96 offset1:128
	ds_write2_b32 v136, v112, v113 offset0:104 offset1:136
	ds_write2_b32 v135, v114, v115 offset0:108 offset1:140
	v_add_u32_e32 v143, 0x400, v82
	v_add_u32_e32 v142, 0x1000, v82
	v_add_u32_e32 v141, 0x1200, v82
	v_add_u32_e32 v140, 0x1400, v82
	v_add_u32_e32 v139, 0x1600, v82
	v_add_u32_e32 v138, 0x2000, v82
	v_add_u32_e32 v137, 0x2400, v82
	v_add_u32_e32 v136, 0x2800, v82
	v_add_u32_e32 v135, 0x3000, v82
	v_add_u32_e32 v134, 0x3400, v82
	v_add_u32_e32 v133, 0x3800, v82
	ds_read2_b32 v[84:85], v82 offset0:64 offset1:96
	ds_read2_b32 v[86:87], v82 offset0:196 offset1:228
	ds_read2_b32 v[88:89], v143 offset0:204 offset1:236
	ds_read2_b32 v[90:91], v141 offset0:100 offset1:132
	ds_read2_b32 v[92:93], v143 offset0:72 offset1:104
	ds_read2_b32 v[94:95], v139 offset0:108 offset1:140
	ds_read2_b32 v[96:97], v142 offset0:96 offset1:128
	ds_read2_b32 v[98:99], v137 offset0:4 offset1:36
	ds_read2_b32 v[100:101], v136 offset0:12 offset1:44
	ds_read2_b32 v[102:103], v140 offset0:104 offset1:136
	ds_read2_b32 v[104:105], v134 offset0:36 offset1:68
	ds_read2_b32 v[106:107], v138 offset0:128 offset1:160
	ds_read2_b32 v[108:109], v137 offset0:136 offset1:168
	ds_read2_b32 v[110:111], v135 offset0:160 offset1:192
	ds_read2_b32 v[112:113], v134 offset0:168 offset1:200
	ds_read2_b32 v[114:115], v133 offset0:44 offset1:76
	s_waitcnt lgkmcnt(0)
	v_fma_f32 v84, v18, v66, -v84
	v_fma_f32 v85, v2, v66, -v85
	v_fma_f32 v86, v19, v70, -v86
	v_fma_f32 v87, v3, v70, -v87
	v_fma_f32 v88, v21, v68, -v88
	v_fma_f32 v89, v5, v68, -v89
	v_fma_f32 v90, v23, v73, -v90
	v_fma_f32 v91, v7, v73, -v91
	v_fma_f32 v92, v20, v69, -v92
	v_fma_f32 v93, v4, v69, -v93
	v_fma_f32 v94, v25, v71, -v94
	v_fma_f32 v95, v9, v71, -v95
	v_fma_f32 v96, v22, v67, -v96
	v_fma_f32 v97, v6, v67, -v97
	v_fma_f32 v98, v27, v76, -v98
	v_fma_f32 v99, v11, v76, -v99
	v_fma_f32 v100, v29, v74, -v100
	v_fma_f32 v101, v13, v74, -v101
	v_fma_f32 v102, v24, v72, -v102
	v_fma_f32 v103, v8, v72, -v103
	v_fma_f32 v104, v31, v80, -v104
	v_fma_f32 v105, v15, v80, -v105
	v_fma_f32 v106, v26, v77, -v106
	v_fma_f32 v107, v10, v77, -v107
	v_fma_f32 v108, v28, v75, -v108
	v_fma_f32 v109, v12, v75, -v109
	v_fma_f32 v110, v30, v81, -v110
	v_fma_f32 v111, v14, v81, -v111
	v_fma_f32 v112, v32, v79, -v112
	v_fma_f32 v113, v16, v79, -v113
	v_fma_f32 v114, v33, v78, -v114
	v_fma_f32 v115, v17, v78, -v115
	ds_write2_b32 v82, v84, v85 offset0:64 offset1:96
	ds_write2_b32 v82, v86, v87 offset0:196 offset1:228
	ds_write2_b32 v143, v88, v89 offset0:204 offset1:236
	ds_write2_b32 v141, v90, v91 offset0:100 offset1:132
	ds_write2_b32 v143, v92, v93 offset0:72 offset1:104
	ds_write2_b32 v139, v94, v95 offset0:108 offset1:140
	ds_write2_b32 v142, v96, v97 offset0:96 offset1:128
	ds_write2_b32 v137, v98, v99 offset0:4 offset1:36
	ds_write2_b32 v136, v100, v101 offset0:12 offset1:44
	ds_write2_b32 v140, v102, v103 offset0:104 offset1:136
	ds_write2_b32 v134, v104, v105 offset0:36 offset1:68
	ds_write2_b32 v138, v106, v107 offset0:128 offset1:160
	ds_write2_b32 v137, v108, v109 offset0:136 offset1:168
	ds_write2_b32 v135, v110, v111 offset0:160 offset1:192
	ds_write2_b32 v134, v112, v113 offset0:168 offset1:200
	ds_write2_b32 v133, v114, v115 offset0:44 offset1:76
	v_mul_u32_u24_e32 v2, 0x210, v199
	v_lshlrev_b32_e32 v82, 8, v198
	s_waitcnt lgkmcnt(0)
	v_add3_u32 v71, s14, v2, v82
	ds_read_b128 v[50:53], v71
	ds_read_b128 v[46:49], v71 offset:16
	ds_read_b128 v[26:29], v71 offset:32
	ds_read_b128 v[18:21], v71 offset:48
	ds_read_b128 v[30:33], v71 offset:64
	s_waitcnt lgkmcnt(4)
	v_pk_mul_f32 v[2:3], v[52:53], v[52:53]
	v_pk_mul_f32 v[4:5], v[50:51], v[50:51]
	ds_read_b128 v[42:45], v71 offset:80
	v_pk_mov_b32 v[6:7], v[4:5], v[2:3] op_sel:[1,0]
	v_mov_b32_e32 v5, v3
	v_pk_add_f32 v[2:3], v[6:7], v[4:5]
	s_waitcnt lgkmcnt(4)
	v_pk_mul_f32 v[4:5], v[48:49], v[48:49]
	v_pk_mul_f32 v[6:7], v[46:47], v[46:47]
	v_pk_add_f32 v[2:3], v[2:3], v[2:3] op_sel:[0,1] op_sel_hi:[1,0]
	v_pk_mov_b32 v[8:9], v[6:7], v[4:5] op_sel:[1,0]
	v_mov_b32_e32 v7, v5
	v_pk_add_f32 v[4:5], v[8:9], v[6:7]
	s_waitcnt lgkmcnt(3)
	v_pk_mul_f32 v[6:7], v[28:29], v[28:29]
	v_pk_add_f32 v[4:5], v[4:5], v[4:5] op_sel:[0,1] op_sel_hi:[1,0]
	v_pk_mul_f32 v[8:9], v[26:27], v[26:27]
	s_waitcnt lgkmcnt(2)
	v_pk_mul_f32 v[10:11], v[20:21], v[20:21]
	v_pk_mul_f32 v[12:13], v[18:19], v[18:19]
	v_add_f32_e32 v8, v8, v9
	v_add_f32_e32 v6, v6, v7
	v_mov_b32_e32 v3, v12
	v_mov_b32_e32 v5, v13
	v_mov_b32_e32 v9, v10
	v_mov_b32_e32 v7, v11
	ds_read_b128 v[38:41], v71 offset:96
	v_pk_add_f32 v[2:3], v[2:3], v[4:5]
	v_pk_add_f32 v[4:5], v[8:9], v[6:7]
	s_waitcnt lgkmcnt(2)
	v_pk_mul_f32 v[6:7], v[30:31], v[30:31]
	v_pk_add_f32 v[2:3], v[2:3], v[4:5]
	v_pk_mul_f32 v[4:5], v[32:33], v[32:33]
	ds_read_b128 v[54:57], v71 offset:112
	v_pk_mov_b32 v[8:9], v[6:7], v[4:5] op_sel:[1,0]
	v_mov_b32_e32 v7, v5
	v_pk_add_f32 v[4:5], v[8:9], v[6:7]
	v_pk_add_f32 v[2:3], v[2:3], v[2:3] op_sel:[0,1] op_sel_hi:[1,0]
	v_pk_add_f32 v[4:5], v[4:5], v[4:5] op_sel:[0,1] op_sel_hi:[1,0]
	s_waitcnt lgkmcnt(2)
	v_pk_mul_f32 v[6:7], v[44:45], v[44:45]
	v_pk_mul_f32 v[8:9], v[42:43], v[42:43]
	s_waitcnt lgkmcnt(1)
	v_pk_mul_f32 v[10:11], v[40:41], v[40:41]
	v_pk_mul_f32 v[12:13], v[38:39], v[38:39]
	v_add_f32_e32 v8, v8, v9
	v_add_f32_e32 v6, v6, v7
	v_mov_b32_e32 v3, v12
	v_mov_b32_e32 v5, v13
	v_mov_b32_e32 v9, v10
	v_mov_b32_e32 v7, v11
	ds_read_b128 v[58:61], v71 offset:128
	ds_read_b128 v[62:65], v71 offset:144
	v_pk_add_f32 v[2:3], v[2:3], v[4:5]
	v_pk_add_f32 v[4:5], v[8:9], v[6:7]
	s_waitcnt lgkmcnt(2)
	v_pk_mul_f32 v[6:7], v[54:55], v[54:55]
	v_pk_add_f32 v[2:3], v[2:3], v[4:5]
	v_pk_mul_f32 v[4:5], v[56:57], v[56:57]
	ds_read_b128 v[34:37], v71 offset:160
	v_pk_mov_b32 v[8:9], v[6:7], v[4:5] op_sel:[1,0]
	v_mov_b32_e32 v7, v5
	v_pk_add_f32 v[4:5], v[8:9], v[6:7]
	v_pk_add_f32 v[2:3], v[2:3], v[2:3] op_sel:[0,1] op_sel_hi:[1,0]
	v_pk_add_f32 v[4:5], v[4:5], v[4:5] op_sel:[0,1] op_sel_hi:[1,0]
	s_waitcnt lgkmcnt(2)
	v_pk_mul_f32 v[6:7], v[60:61], v[60:61]
	v_pk_mul_f32 v[8:9], v[58:59], v[58:59]
	s_waitcnt lgkmcnt(1)
	v_pk_mul_f32 v[10:11], v[64:65], v[64:65]
	v_pk_mul_f32 v[12:13], v[62:63], v[62:63]
	v_add_f32_e32 v8, v8, v9
	v_add_f32_e32 v6, v6, v7
	v_mov_b32_e32 v3, v12
	v_mov_b32_e32 v5, v13
	v_mov_b32_e32 v9, v10
	v_mov_b32_e32 v7, v11
	ds_read_b128 v[22:25], v71 offset:176
	ds_read_b128 v[14:17], v71 offset:192
	v_pk_add_f32 v[2:3], v[2:3], v[4:5]
	v_pk_add_f32 v[4:5], v[8:9], v[6:7]
	s_waitcnt lgkmcnt(2)
	v_pk_mul_f32 v[6:7], v[34:35], v[34:35]
	v_pk_add_f32 v[2:3], v[2:3], v[4:5]
	v_pk_mul_f32 v[4:5], v[36:37], v[36:37]
	v_pk_add_f32 v[2:3], v[2:3], v[2:3] op_sel:[0,1] op_sel_hi:[1,0]
	v_pk_mov_b32 v[8:9], v[6:7], v[4:5] op_sel:[1,0]
	v_mov_b32_e32 v7, v5
	v_pk_add_f32 v[4:5], v[8:9], v[6:7]
	s_waitcnt lgkmcnt(1)
	v_pk_mul_f32 v[6:7], v[24:25], v[24:25]
	v_pk_add_f32 v[4:5], v[4:5], v[4:5] op_sel:[0,1] op_sel_hi:[1,0]
	v_pk_mul_f32 v[8:9], v[22:23], v[22:23]
	s_waitcnt lgkmcnt(0)
	v_pk_mul_f32 v[10:11], v[16:17], v[16:17]
	v_pk_mul_f32 v[12:13], v[14:15], v[14:15]
	v_add_f32_e32 v8, v8, v9
	v_add_f32_e32 v6, v6, v7
	v_mov_b32_e32 v3, v12
	v_mov_b32_e32 v5, v13
	v_mov_b32_e32 v9, v10
	v_mov_b32_e32 v7, v11
	ds_read_b128 v[10:13], v71 offset:208
	v_pk_add_f32 v[2:3], v[2:3], v[4:5]
	v_pk_add_f32 v[4:5], v[8:9], v[6:7]
	s_nop 0
	v_pk_add_f32 v[2:3], v[2:3], v[4:5]
	s_waitcnt lgkmcnt(0)
	v_pk_mul_f32 v[4:5], v[10:11], v[10:11]
	v_pk_add_f32 v[66:67], v[2:3], v[2:3] op_sel:[0,1] op_sel_hi:[1,0]
	v_pk_mul_f32 v[2:3], v[12:13], v[12:13]
	s_nop 0
	v_pk_mov_b32 v[6:7], v[4:5], v[2:3] op_sel:[1,0]
	v_mov_b32_e32 v5, v3
	v_pk_add_f32 v[2:3], v[6:7], v[4:5]
	ds_read_b128 v[6:9], v71 offset:224
	v_pk_add_f32 v[68:69], v[2:3], v[2:3] op_sel:[0,1] op_sel_hi:[1,0]
	s_waitcnt lgkmcnt(0)
	v_pk_mul_f32 v[2:3], v[8:9], v[8:9]
	v_pk_mul_f32 v[4:5], v[6:7], v[6:7]
	v_add_f32_e32 v72, v2, v3
	v_add_f32_e32 v70, v4, v5
	ds_read_b128 v[2:5], v71 offset:240
	s_waitcnt lgkmcnt(0)
	v_pk_mul_f32 v[74:75], v[4:5], v[4:5]
	v_pk_mul_f32 v[76:77], v[2:3], v[2:3]
	v_mov_b32_e32 v71, v74
	v_mov_b32_e32 v67, v76
	v_mov_b32_e32 v69, v77
	v_mov_b32_e32 v73, v75
	v_pk_add_f32 v[66:67], v[66:67], v[68:69]
	v_pk_add_f32 v[68:69], v[70:71], v[72:73]
	s_nop 0
	v_pk_add_f32 v[66:67], v[66:67], v[68:69]
	s_nop 0
	v_add_f32_e32 v66, v66, v67
	ds_bpermute_b32 v0, v0, v66
	s_waitcnt lgkmcnt(0)
	v_add_f32_e32 v0, v66, v0
	v_lshl_or_b32 v66, v198, 6, s67
	v_or_b32_e32 v186, v66, v186
	v_lshlrev_b64 v[66:67], 1, v[186:187]
	v_lshl_add_u64 v[80:81], s[18:19], 0, v[66:67]
	v_lshl_add_u64 v[78:79], s[16:17], 0, v[66:67]
	global_load_dwordx4 v[98:101], v82, s[42:43]
	global_load_dwordx4 v[102:105], v82, s[42:43] offset:16
	global_load_dwordx4 v[106:109], v82, s[42:43] offset:32
	global_load_dwordx4 v[110:113], v82, s[42:43] offset:48
	global_load_dwordx4 v[114:117], v82, s[42:43] offset:64
	global_load_dwordx4 v[118:121], v82, s[42:43] offset:80
	global_load_dwordx4 v[122:125], v82, s[42:43] offset:96
	global_load_dwordx4 v[126:129], v82, s[42:43] offset:112
	global_load_dwordx4 v[130:133], v82, s[42:43] offset:128
	global_load_dwordx4 v[134:137], v82, s[42:43] offset:144
	global_load_dwordx4 v[138:141], v82, s[42:43] offset:160
	global_load_dwordx4 v[142:145], v82, s[42:43] offset:176
	global_load_dwordx4 v[66:69], v82, s[42:43] offset:192
	global_load_dwordx4 v[70:73], v82, s[42:43] offset:208
	global_load_dwordx4 v[74:77], v82, s[42:43] offset:224
	global_load_dwordx4 v[84:87], v82, s[42:43] offset:240
	v_fmamk_f32 v0, v0, 0x3c000000, v211
	v_rsq_f32_e32 v0, v0
	s_nop 0
	v_mul_f32_e32 v0, v197, v0
	v_pk_mul_f32 v[50:51], v[50:51], v[0:1] op_sel_hi:[1,0]
	v_pk_mul_f32 v[46:47], v[46:47], v[0:1] op_sel_hi:[1,0]
	v_pk_mul_f32 v[48:49], v[48:49], v[0:1] op_sel_hi:[1,0]
	v_pk_mul_f32 v[52:53], v[52:53], v[0:1] op_sel_hi:[1,0]
	v_pk_mul_f32 v[26:27], v[26:27], v[0:1] op_sel_hi:[1,0]
	v_pk_mul_f32 v[18:19], v[18:19], v[0:1] op_sel_hi:[1,0]
	v_pk_mul_f32 v[20:21], v[20:21], v[0:1] op_sel_hi:[1,0]
	v_pk_mul_f32 v[28:29], v[28:29], v[0:1] op_sel_hi:[1,0]
	v_pk_mul_f32 v[30:31], v[30:31], v[0:1] op_sel_hi:[1,0]
	v_pk_mul_f32 v[42:43], v[42:43], v[0:1] op_sel_hi:[1,0]
	v_pk_mul_f32 v[32:33], v[32:33], v[0:1] op_sel_hi:[1,0]
	v_pk_mul_f32 v[44:45], v[44:45], v[0:1] op_sel_hi:[1,0]
	v_pk_mul_f32 v[38:39], v[38:39], v[0:1] op_sel_hi:[1,0]
	v_pk_mul_f32 v[40:41], v[40:41], v[0:1] op_sel_hi:[1,0]
	v_pk_mul_f32 v[34:35], v[34:35], v[0:1] op_sel_hi:[1,0]
	v_pk_mul_f32 v[22:23], v[22:23], v[0:1] op_sel_hi:[1,0]
	v_pk_mul_f32 v[36:37], v[36:37], v[0:1] op_sel_hi:[1,0]
	v_pk_mul_f32 v[24:25], v[24:25], v[0:1] op_sel_hi:[1,0]
	v_pk_mul_f32 v[14:15], v[14:15], v[0:1] op_sel_hi:[1,0]
	v_pk_mul_f32 v[10:11], v[10:11], v[0:1] op_sel_hi:[1,0]
	v_pk_mul_f32 v[12:13], v[12:13], v[0:1] op_sel_hi:[1,0]
	v_pk_mul_f32 v[16:17], v[16:17], v[0:1] op_sel_hi:[1,0]
	v_pk_mul_f32 v[6:7], v[6:7], v[0:1] op_sel_hi:[1,0]
	v_pk_mul_f32 v[2:3], v[2:3], v[0:1] op_sel_hi:[1,0]
	v_pk_mul_f32 v[4:5], v[4:5], v[0:1] op_sel_hi:[1,0]
	v_pk_mul_f32 v[8:9], v[8:9], v[0:1] op_sel_hi:[1,0]
	v_pk_mul_f32 v[54:55], v[54:55], v[0:1] op_sel_hi:[1,0]
	v_pk_mul_f32 v[56:57], v[56:57], v[0:1] op_sel_hi:[1,0]
	v_pk_mul_f32 v[58:59], v[58:59], v[0:1] op_sel_hi:[1,0]
	v_pk_mul_f32 v[60:61], v[60:61], v[0:1] op_sel_hi:[1,0]
	v_pk_mul_f32 v[62:63], v[62:63], v[0:1] op_sel_hi:[1,0]
	v_pk_mul_f32 v[64:65], v[64:65], v[0:1] op_sel_hi:[1,0]
	s_waitcnt vmcnt(14)
	v_pk_mul_f32 v[50:51], v[98:99], v[50:51]
	v_pk_mul_f32 v[52:53], v[100:101], v[52:53]
	v_pk_mul_f32 v[46:47], v[102:103], v[46:47]
	v_pk_mul_f32 v[48:49], v[104:105], v[48:49]
	v_lshlrev_b32_e32 v88, 16, v146
	v_and_b32_e32 v146, 0xffff0000, v146
	v_lshlrev_b32_e32 v89, 16, v147
	v_and_b32_e32 v147, 0xffff0000, v147
	v_lshlrev_b32_e32 v90, 16, v148
	v_and_b32_e32 v148, 0xffff0000, v148
	v_lshlrev_b32_e32 v91, 16, v149
	v_and_b32_e32 v149, 0xffff0000, v149
	v_mul_f32_e32 v88, v50, v88
	v_mul_f32_e32 v146, v51, v146
	v_mul_f32_e32 v89, v52, v89
	v_mul_f32_e32 v147, v53, v147
	v_mul_f32_e32 v90, v46, v90
	v_mul_f32_e32 v148, v47, v148
	v_mul_f32_e32 v91, v48, v91
	v_mul_f32_e32 v149, v49, v149
	v_cvt_pk_bf16_f32 v146, v88, v146
	v_cvt_pk_bf16_f32 v147, v89, v147
	v_cvt_pk_bf16_f32 v148, v90, v148
	v_cvt_pk_bf16_f32 v149, v91, v149
	global_store_dwordx4 v[78:79], v[146:149], off
	s_waitcnt vmcnt(13)
	v_pk_mul_f32 v[26:27], v[106:107], v[26:27]
	v_pk_mul_f32 v[28:29], v[108:109], v[28:29]
	v_pk_mul_f32 v[18:19], v[110:111], v[18:19]
	v_pk_mul_f32 v[20:21], v[112:113], v[20:21]
	v_lshlrev_b32_e32 v88, 16, v150
	v_and_b32_e32 v150, 0xffff0000, v150
	v_lshlrev_b32_e32 v89, 16, v151
	v_and_b32_e32 v151, 0xffff0000, v151
	v_lshlrev_b32_e32 v90, 16, v152
	v_and_b32_e32 v152, 0xffff0000, v152
	v_lshlrev_b32_e32 v91, 16, v153
	v_and_b32_e32 v153, 0xffff0000, v153
	v_mul_f32_e32 v88, v26, v88
	v_mul_f32_e32 v150, v27, v150
	v_mul_f32_e32 v89, v28, v89
	v_mul_f32_e32 v151, v29, v151
	v_mul_f32_e32 v90, v18, v90
	v_mul_f32_e32 v152, v19, v152
	v_mul_f32_e32 v91, v20, v91
	v_mul_f32_e32 v153, v21, v153
	v_cvt_pk_bf16_f32 v150, v88, v150
	v_cvt_pk_bf16_f32 v151, v89, v151
	v_cvt_pk_bf16_f32 v152, v90, v152
	v_cvt_pk_bf16_f32 v153, v91, v153
	global_store_dwordx4 v[78:79], v[150:153], off offset:16
	s_waitcnt vmcnt(12)
	v_pk_mul_f32 v[30:31], v[114:115], v[30:31]
	v_pk_mul_f32 v[32:33], v[116:117], v[32:33]
	v_pk_mul_f32 v[42:43], v[118:119], v[42:43]
	v_pk_mul_f32 v[44:45], v[120:121], v[44:45]
	v_lshlrev_b32_e32 v88, 16, v154
	v_and_b32_e32 v154, 0xffff0000, v154
	v_lshlrev_b32_e32 v89, 16, v155
	v_and_b32_e32 v155, 0xffff0000, v155
	v_lshlrev_b32_e32 v90, 16, v156
	v_and_b32_e32 v156, 0xffff0000, v156
	v_lshlrev_b32_e32 v91, 16, v157
	v_and_b32_e32 v157, 0xffff0000, v157
	v_mul_f32_e32 v88, v30, v88
	v_mul_f32_e32 v154, v31, v154
	v_mul_f32_e32 v89, v32, v89
	v_mul_f32_e32 v155, v33, v155
	v_mul_f32_e32 v90, v42, v90
	v_mul_f32_e32 v156, v43, v156
	v_mul_f32_e32 v91, v44, v91
	v_mul_f32_e32 v157, v45, v157
	v_cvt_pk_bf16_f32 v154, v88, v154
	v_cvt_pk_bf16_f32 v155, v89, v155
	v_cvt_pk_bf16_f32 v156, v90, v156
	v_cvt_pk_bf16_f32 v157, v91, v157
	global_store_dwordx4 v[78:79], v[154:157], off offset:32
	s_waitcnt vmcnt(11)
	v_pk_mul_f32 v[38:39], v[122:123], v[38:39]
	v_pk_mul_f32 v[40:41], v[124:125], v[40:41]
	v_pk_mul_f32 v[54:55], v[126:127], v[54:55]
	v_pk_mul_f32 v[56:57], v[128:129], v[56:57]
	v_lshlrev_b32_e32 v88, 16, v158
	v_and_b32_e32 v158, 0xffff0000, v158
	v_lshlrev_b32_e32 v89, 16, v159
	v_and_b32_e32 v159, 0xffff0000, v159
	v_lshlrev_b32_e32 v90, 16, v160
	v_and_b32_e32 v160, 0xffff0000, v160
	v_lshlrev_b32_e32 v91, 16, v161
	v_and_b32_e32 v161, 0xffff0000, v161
	v_mul_f32_e32 v88, v38, v88
	v_mul_f32_e32 v158, v39, v158
	v_mul_f32_e32 v89, v40, v89
	v_mul_f32_e32 v159, v41, v159
	v_mul_f32_e32 v90, v54, v90
	v_mul_f32_e32 v160, v55, v160
	v_mul_f32_e32 v91, v56, v91
	v_mul_f32_e32 v161, v57, v161
	v_cvt_pk_bf16_f32 v158, v88, v158
	v_cvt_pk_bf16_f32 v159, v89, v159
	v_cvt_pk_bf16_f32 v160, v90, v160
	v_cvt_pk_bf16_f32 v161, v91, v161
	global_store_dwordx4 v[78:79], v[158:161], off offset:48
	s_waitcnt vmcnt(10)
	v_pk_mul_f32 v[58:59], v[130:131], v[58:59]
	v_pk_mul_f32 v[60:61], v[132:133], v[60:61]
	v_pk_mul_f32 v[62:63], v[134:135], v[62:63]
	v_pk_mul_f32 v[64:65], v[136:137], v[64:65]
	v_lshlrev_b32_e32 v88, 16, v162
	v_and_b32_e32 v162, 0xffff0000, v162
	v_lshlrev_b32_e32 v89, 16, v163
	v_and_b32_e32 v163, 0xffff0000, v163
	v_lshlrev_b32_e32 v90, 16, v164
	v_and_b32_e32 v164, 0xffff0000, v164
	v_lshlrev_b32_e32 v91, 16, v165
	v_and_b32_e32 v165, 0xffff0000, v165
	v_mul_f32_e32 v88, v58, v88
	v_mul_f32_e32 v162, v59, v162
	v_mul_f32_e32 v89, v60, v89
	v_mul_f32_e32 v163, v61, v163
	v_mul_f32_e32 v90, v62, v90
	v_mul_f32_e32 v164, v63, v164
	v_mul_f32_e32 v91, v64, v91
	v_mul_f32_e32 v165, v65, v165
	v_cvt_pk_bf16_f32 v162, v88, v162
	v_cvt_pk_bf16_f32 v163, v89, v163
	v_cvt_pk_bf16_f32 v164, v90, v164
	v_cvt_pk_bf16_f32 v165, v91, v165
	global_store_dwordx4 v[78:79], v[162:165], off offset:64
	s_waitcnt vmcnt(9)
	v_pk_mul_f32 v[34:35], v[138:139], v[34:35]
	v_pk_mul_f32 v[36:37], v[140:141], v[36:37]
	v_pk_mul_f32 v[22:23], v[142:143], v[22:23]
	v_pk_mul_f32 v[24:25], v[144:145], v[24:25]
	v_lshlrev_b32_e32 v88, 16, v166
	v_and_b32_e32 v166, 0xffff0000, v166
	v_lshlrev_b32_e32 v89, 16, v167
	v_and_b32_e32 v167, 0xffff0000, v167
	v_lshlrev_b32_e32 v90, 16, v168
	v_and_b32_e32 v168, 0xffff0000, v168
	v_lshlrev_b32_e32 v91, 16, v169
	v_and_b32_e32 v169, 0xffff0000, v169
	v_mul_f32_e32 v88, v34, v88
	v_mul_f32_e32 v166, v35, v166
	v_mul_f32_e32 v89, v36, v89
	v_mul_f32_e32 v167, v37, v167
	v_mul_f32_e32 v90, v22, v90
	v_mul_f32_e32 v168, v23, v168
	v_mul_f32_e32 v91, v24, v91
	v_mul_f32_e32 v169, v25, v169
	v_cvt_pk_bf16_f32 v166, v88, v166
	v_cvt_pk_bf16_f32 v167, v89, v167
	v_cvt_pk_bf16_f32 v168, v90, v168
	v_cvt_pk_bf16_f32 v169, v91, v169
	global_store_dwordx4 v[78:79], v[166:169], off offset:80
	s_waitcnt vmcnt(8)
	v_pk_mul_f32 v[14:15], v[66:67], v[14:15]
	v_pk_mul_f32 v[16:17], v[68:69], v[16:17]
	v_pk_mul_f32 v[10:11], v[70:71], v[10:11]
	v_pk_mul_f32 v[12:13], v[72:73], v[12:13]
	v_lshlrev_b32_e32 v88, 16, v170
	v_and_b32_e32 v170, 0xffff0000, v170
	v_lshlrev_b32_e32 v89, 16, v171
	v_and_b32_e32 v171, 0xffff0000, v171
	v_lshlrev_b32_e32 v90, 16, v172
	v_and_b32_e32 v172, 0xffff0000, v172
	v_lshlrev_b32_e32 v91, 16, v173
	v_and_b32_e32 v173, 0xffff0000, v173
	v_mul_f32_e32 v88, v14, v88
	v_mul_f32_e32 v170, v15, v170
	v_mul_f32_e32 v89, v16, v89
	v_mul_f32_e32 v171, v17, v171
	v_mul_f32_e32 v90, v10, v90
	v_mul_f32_e32 v172, v11, v172
	v_mul_f32_e32 v91, v12, v91
	v_mul_f32_e32 v173, v13, v173
	v_cvt_pk_bf16_f32 v170, v88, v170
	v_cvt_pk_bf16_f32 v171, v89, v171
	v_cvt_pk_bf16_f32 v172, v90, v172
	v_cvt_pk_bf16_f32 v173, v91, v173
	global_store_dwordx4 v[78:79], v[170:173], off offset:96
	s_waitcnt vmcnt(7)
	v_pk_mul_f32 v[6:7], v[74:75], v[6:7]
	v_pk_mul_f32 v[8:9], v[76:77], v[8:9]
	v_pk_mul_f32 v[2:3], v[84:85], v[2:3]
	v_pk_mul_f32 v[4:5], v[86:87], v[4:5]
	v_lshlrev_b32_e32 v88, 16, v174
	v_and_b32_e32 v174, 0xffff0000, v174
	v_lshlrev_b32_e32 v89, 16, v175
	v_and_b32_e32 v175, 0xffff0000, v175
	v_lshlrev_b32_e32 v90, 16, v176
	v_and_b32_e32 v176, 0xffff0000, v176
	v_lshlrev_b32_e32 v91, 16, v177
	v_and_b32_e32 v177, 0xffff0000, v177
	v_mul_f32_e32 v88, v6, v88
	v_mul_f32_e32 v174, v7, v174
	v_mul_f32_e32 v89, v8, v89
	v_mul_f32_e32 v175, v9, v175
	v_mul_f32_e32 v90, v2, v90
	v_mul_f32_e32 v176, v3, v176
	v_mul_f32_e32 v91, v4, v91
	v_mul_f32_e32 v177, v5, v177
	v_cvt_pk_bf16_f32 v174, v88, v174
	v_cvt_pk_bf16_f32 v175, v89, v175
	v_cvt_pk_bf16_f32 v176, v90, v176
	v_cvt_pk_bf16_f32 v177, v91, v177
	global_store_dwordx4 v[78:79], v[174:177], off offset:112
	s_branch .LBB0_266
